# RSTD cache fill at GEMM phase start: per-slot ssq loads issued without waiting, reduce+LDS write deferred until after the first stage loads (overlaps 2-3 serial load round trips)
# speedup vs baseline: 1.0051x; 1.0051x over previous
; #define PG8_LAS __attribute__((address_space(3)))
;     __device__ __forceinline__ float rstd_global(int row) const { return row_rstd(ssq, row); }
;     __device__ __forceinline__ float rstd_global(int row) const { return row_rstd(ssq, row); }
;     __device__ __forceinline__ float rstd_global(int row) const { return row_rstd(ssq, row); }
; template <class Epi, class Sched, bool ALIGN_EPI = false, bool SP2 = false>
; __device__ __forceinline__ void gemm_phase(PG8_LAS unsigned char* lds, const Gemm g, const Sched& S, const Epi& E) {
;     ...
;     if constexpr (Epi::RSTD) {
;         PG8_LAS float* rt = (PG8_LAS float*)(lds + STAGE_BYTES);
;         Unit tu;
;         for (int i = 0; S.next(i, tu); ++i) {
;             const int p = tu.pm;
;             if (p != pmc0 && p != pmc1 && p != pmc2 && p != pmc3) {
;                 int slot = -1;
;                 if (pmc0 < 0) { pmc0 = p; slot = 0; } else if (pmc1 < 0) { pmc1 = p; slot = 1; } else if (pmc2 < 0) { pmc2 = p; slot = 2; } else if (pmc3 < 0) { pmc3 = p; slot = 3; }
;                 if (slot >= 0 && tid < 256) rt[slot * 256 + tid] = E.rstd_global(p * 256 + tid);
;             }
;         }
;     }
; __device__ __forceinline__ float row_rstd(const float* ssq, int row) {
;     const float* p = ssq + (size_t)row * 16;
;     const f32x4 a = gld<f32x4>(p), b = gld<f32x4>(p + 4), c = gld<f32x4>(p + 8), d = gld<f32x4>(p + 12);
;     const f32x4 s = (a + b) + (c + d);
;     const float t = (s[0] + s[1]) + (s[2] + s[3]);
;     return __builtin_amdgcn_rsqf(t * (1.f / 1024.f) + RMS_EPS);
; }
.LBB0_134:
	s_andn2_b64 vcc, exec, s[0:1]
	s_cbranch_vccnz .LBB0_210
	v_readlane_b32 s0, v253, 3
	v_mov_b32_e32 v4, v232
	v_readlane_b32 s1, v253, 4
	s_andn2_b64 vcc, exec, s[0:1]
	v_readfirstlane_b32 s26, v4
	s_cbranch_vccnz .LBB0_210
	v_writelane_b32 v255, s96, 35
	v_readlane_b32 s0, v254, 39
	s_add_u32 s40, s54, 0x6a00000
	v_writelane_b32 v255, s97, 36
	v_writelane_b32 v255, s31, 17
	v_writelane_b32 v255, s38, 19
	v_lshl_add_u32 v0, v4, 2, s0
	s_movk_i32 s0, 0x100
	v_readlane_b32 s12, v254, 21
	v_writelane_b32 v255, s39, 20
	s_addc_u32 s41, s55, 0
	v_cmp_gt_i32_e64 s[0:1], s0, v4
	s_mov_b32 s3, -1
	v_readlane_b32 s13, v254, 22
	s_mov_b32 s10, -1
	s_mov_b32 s11, -1
	s_mov_b32 s4, -1
	s_mov_b32 s101, 0
	s_branch .LBB0_141
.LrsA_ld0:
	v_lshl_add_u32 v2, s2, 8, v4
	v_ashrrev_i32_e32 v3, 31, v2
	v_lshlrev_b64 v[2:3], 6, v[2:3]
	v_lshl_add_u64 v[2:3], s[40:41], 0, v[2:3]
	s_bitset1_b32 s101, 0
	global_load_dwordx4 v[24:27], v[2:3], off
	global_load_dwordx4 v[28:31], v[2:3], off offset:16
	global_load_dwordx4 v[32:35], v[2:3], off offset:32
	global_load_dwordx4 v[36:39], v[2:3], off offset:48
	s_branch .LBB0_138
.LrsA_ld1:
	v_lshl_add_u32 v2, s2, 8, v4
	v_ashrrev_i32_e32 v3, 31, v2
	v_lshlrev_b64 v[2:3], 6, v[2:3]
	v_lshl_add_u64 v[2:3], s[40:41], 0, v[2:3]
	s_bitset1_b32 s101, 1
	global_load_dwordx4 v[40:43], v[2:3], off
	global_load_dwordx4 v[44:47], v[2:3], off offset:16
	global_load_dwordx4 v[48:51], v[2:3], off offset:32
	global_load_dwordx4 v[52:55], v[2:3], off offset:48
	s_branch .LBB0_138
.LrsA_ld2:
	v_lshl_add_u32 v2, s2, 8, v4
	v_ashrrev_i32_e32 v3, 31, v2
	v_lshlrev_b64 v[2:3], 6, v[2:3]
	v_lshl_add_u64 v[2:3], s[40:41], 0, v[2:3]
	s_bitset1_b32 s101, 2
	global_load_dwordx4 v[56:59], v[2:3], off
	global_load_dwordx4 v[60:63], v[2:3], off offset:16
	global_load_dwordx4 v[64:67], v[2:3], off offset:32
	global_load_dwordx4 v[68:71], v[2:3], off offset:48
	s_branch .LBB0_138
.LrsA_ld3:
	v_lshl_add_u32 v2, s2, 8, v4
	v_ashrrev_i32_e32 v3, 31, v2
	v_lshlrev_b64 v[2:3], 6, v[2:3]
	v_lshl_add_u64 v[2:3], s[40:41], 0, v[2:3]
	s_bitset1_b32 s101, 3
	global_load_dwordx4 v[72:75], v[2:3], off
	global_load_dwordx4 v[76:79], v[2:3], off offset:16
	global_load_dwordx4 v[80:83], v[2:3], off offset:32
	global_load_dwordx4 v[84:87], v[2:3], off offset:48

; #define PG8_STAGE(bufoff, gbase, voff) do { _Pragma("unroll") for (int _i = 0; _i < 2; ++_i) \
;         __builtin_amdgcn_global_load_lds((const unsigned*)((const char*)(gbase) + (voff)[_i]), (PG8_LAS unsigned*)(lds + (bufoff) + ldsw + _i * 8192), 16, 0, 0); } while (0)
; #define PG8_WAIT_V(n) asm volatile("s_waitcnt vmcnt(" #n ")" ::: "memory")
; #define PG8_BAR __builtin_amdgcn_s_barrier()
; template <class Epi, class Sched, bool ALIGN_EPI = false, bool SP2 = false>
; __device__ __forceinline__ void gemm_phase(PG8_LAS unsigned char* lds, const Gemm g, const Sched& S, const Epi& E) {
;     ...
;         PG8_STAGE(PG8_SB(0, 0), cB, voffB); PG8_STAGE(PG8_SB(0, 1), cB + hstepB, voffB); PG8_STAGE(PG8_SA(0, 0), cA, voffA); PG8_STAGE(PG8_SA(0, 1), cA + hstepA, voffA);
;         if (wr == 1) PG8_BAR;
;         PG8_WAIT_V(2); PG8_BAR;
;         PG8_STAGE(PG8_SB(1, 0), cB + kstepB, voffB); PG8_STAGE(PG8_SA(1, 0), cA + kstepA, voffA); PG8_STAGE(PG8_SB(1, 1), cB + hstepB + kstepB, voffB);
;         PG8_WAIT_V(6); PG8_BAR;
; __device__ __forceinline__ float row_rstd(const float* ssq, int row) {
;     const float* p = ssq + (size_t)row * 16;
;     const f32x4 a = gld<f32x4>(p), b = gld<f32x4>(p + 4), c = gld<f32x4>(p + 8), d = gld<f32x4>(p + 12);
;     const f32x4 s = (a + b) + (c + d);
;     const float t = (s[0] + s[1]) + (s[2] + s[3]);
;     return __builtin_amdgcn_rsqf(t * (1.f / 1024.f) + RMS_EPS);
; }
.LBB0_155:
	s_and_b32 s4, s2, 3
	s_lshl_b32 s98, s3, 6
	v_and_b32_e32 v11, 48, v4
	s_lshl_b32 s2, s3, 13
	v_lshlrev_b32_e32 v12, 6, v4
	s_movk_i32 s3, 0x3c0
	v_lshlrev_b32_e32 v4, 2, v4
	v_and_or_b32 v11, v12, s3, v11
	v_and_b32_e32 v4, 32, v4
	v_bitop3_b32 v12, v11, s2, v4 bitop3:0xde
	v_writelane_b32 v255, s4, 44
	s_lshl_b32 s2, s4, 12
	v_bitop3_b32 v97, v11, s2, v4 bitop3:0xde
	v_readlane_b32 s2, v255, 7
	s_lshl_b32 s4, s2, 6
	s_lshl_b64 s[2:3], s[4:5], 2
	s_add_u32 s97, s78, s2
	s_addc_u32 s38, s79, s3
	s_add_u32 s31, s80, s2
	s_addc_u32 s6, s81, s3
	s_lshl_b32 s2, -1, s58
	s_add_i32 m0, s22, 0x18000
	v_lshl_add_u64 v[2:3], v[2:3], 0, s[36:37]
	s_not_b32 s99, s2
	s_waitcnt vmcnt(2)
	s_barrier
	global_load_lds_dwordx4 v[2:3], off
	s_add_i32 m0, s22, 0x1a000
	s_add_u32 s2, s24, 0x400000
	v_mov_b32_e32 v131, v96
	v_lshl_add_u64 v[0:1], v[0:1], 0, s[36:37]
	s_addc_u32 s3, s25, 0
	s_add_i32 s11, s22, 0x8000
	v_mov_b32_e32 v135, v96
	global_load_lds_dwordx4 v[0:1], off
	v_lshl_add_u64 v[0:1], s[2:3], 0, v[130:131]
	s_mov_b32 m0, s11
	s_add_i32 s19, s22, 0xa000
	global_load_lds_dwordx4 v[0:1], off
	v_lshl_add_u64 v[0:1], s[2:3], 0, v[134:135]
	s_add_u32 s2, s0, 0x40080
	s_mov_b32 m0, s19
	s_addc_u32 s3, s1, 0
	global_load_lds_dwordx4 v[0:1], off
	s_add_i32 m0, s22, 0x1c000
	v_lshl_add_u64 v[0:1], s[2:3], 0, v[132:133]
	global_load_lds_dwordx4 v[0:1], off
	v_lshl_add_u64 v[0:1], s[2:3], 0, v[136:137]
	s_add_i32 m0, s22, 0x1e000
	s_cmpk_lt_u32 s26, 0x100
	global_load_lds_dwordx4 v[0:1], off
	v_lshlrev_b32_e32 v0, 10, v8
	v_and_b32_e32 v0, 0xfffff800, v0
	v_lshl_add_u32 v0, v9, 7, v0
	v_and_b32_e32 v1, 1, v8
	v_lshl_or_b32 v0, v1, 6, v0
	v_lshl_add_u32 v138, v10, 1, v0
	v_lshlrev_b32_e32 v0, 10, v5
	s_cselect_b64 s[2:3], -1, 0
	v_and_b32_e32 v0, 0xfffff800, v0
	s_cmp_eq_u32 s101, 0
	s_cbranch_scc1 .LrsA_done
	v_readlane_b32 s100, v254, 39
	s_waitcnt vmcnt(6)
	s_nop 0
	v_lshl_add_u32 v88, v232, 2, s100
	s_bitcmp1_b32 s101, 0
	s_cbranch_scc0 .LrsA_p1
	v_pk_add_f32 v[26:27], v[26:27], v[30:31]
	v_pk_add_f32 v[24:25], v[24:25], v[28:29]
	v_pk_add_f32 v[34:35], v[34:35], v[38:39]
	v_pk_add_f32 v[32:33], v[32:33], v[36:37]
	v_pk_add_f32 v[26:27], v[26:27], v[34:35]
	v_pk_add_f32 v[24:25], v[24:25], v[32:33]
	s_nop 0
	v_add_f32_e32 v24, v25, v24
	v_add_f32_e32 v26, v26, v27
	v_add_f32_e32 v24, v24, v26
	v_fmamk_f32 v24, v24, 0x3a800000, v251
	v_rsq_f32_e32 v24, v24
	s_nop 1
	ds_write_b32 v88, v24
.LrsA_p1:
	s_bitcmp1_b32 s101, 1
	s_cbranch_scc0 .LrsA_p2
	v_pk_add_f32 v[42:43], v[42:43], v[46:47]
	v_pk_add_f32 v[40:41], v[40:41], v[44:45]
	v_pk_add_f32 v[50:51], v[50:51], v[54:55]
	v_pk_add_f32 v[48:49], v[48:49], v[52:53]
	v_pk_add_f32 v[42:43], v[42:43], v[50:51]
	v_pk_add_f32 v[40:41], v[40:41], v[48:49]
	s_nop 0
	v_add_f32_e32 v40, v41, v40
	v_add_f32_e32 v42, v42, v43
	v_add_f32_e32 v40, v40, v42
	v_fmamk_f32 v40, v40, 0x3a800000, v251
	v_rsq_f32_e32 v40, v40
	s_nop 1
	ds_write_b32 v88, v40 offset:1024
.LrsA_p2:
	s_bitcmp1_b32 s101, 2
	s_cbranch_scc0 .LrsA_p3
	v_pk_add_f32 v[58:59], v[58:59], v[62:63]
	v_pk_add_f32 v[56:57], v[56:57], v[60:61]
	v_pk_add_f32 v[66:67], v[66:67], v[70:71]
	v_pk_add_f32 v[64:65], v[64:65], v[68:69]
	v_pk_add_f32 v[58:59], v[58:59], v[66:67]
	v_pk_add_f32 v[56:57], v[56:57], v[64:65]
	s_nop 0
	v_add_f32_e32 v56, v57, v56
	v_add_f32_e32 v58, v58, v59
	v_add_f32_e32 v56, v56, v58
	v_fmamk_f32 v56, v56, 0x3a800000, v251
	v_rsq_f32_e32 v56, v56
	s_nop 1
	ds_write_b32 v88, v56 offset:2048
.LrsA_p3:
	s_bitcmp1_b32 s101, 3
	s_cbranch_scc0 .LrsA_p4
	v_pk_add_f32 v[74:75], v[74:75], v[78:79]
	v_pk_add_f32 v[72:73], v[72:73], v[76:77]
	v_pk_add_f32 v[82:83], v[82:83], v[86:87]
	v_pk_add_f32 v[80:81], v[80:81], v[84:85]
	v_pk_add_f32 v[74:75], v[74:75], v[82:83]
	v_pk_add_f32 v[72:73], v[72:73], v[80:81]
	s_nop 0
	v_add_f32_e32 v72, v73, v72
	v_add_f32_e32 v74, v74, v75
	v_add_f32_e32 v72, v72, v74
	v_fmamk_f32 v72, v72, 0x3a800000, v251
	v_rsq_f32_e32 v72, v72
	s_nop 1
	ds_write_b32 v88, v72 offset:3072
.LrsA_p4:
.LrsA_done:
	s_waitcnt vmcnt(6)
	v_writelane_b32 v255, s2, 45
	v_lshl_add_u32 v0, v6, 7, v0
	v_and_b32_e32 v1, 1, v5
	v_writelane_b32 v255, s3, 46
	v_lshl_or_b32 v0, v1, 6, v0
	v_readlane_b32 s2, v254, 25
	v_mov_b32_e32 v139, v96
	v_lshl_add_u32 v140, v7, 1, v0
	v_mov_b32_e32 v141, v96
	s_mov_b32 s53, 0
	v_add_u32_e32 v161, 0, v12
	s_mov_b32 s26, s2
	v_readlane_b32 s4, v254, 9
	s_barrier
	v_readlane_b32 s3, v254, 26
	s_branch .LBB0_158

; #define PG8_LAS __attribute__((address_space(3)))
;     __device__ __forceinline__ float rstd_global(int row) const { return row_rstd(ssq, row); }
;     __device__ __forceinline__ float rstd_global(int row) const { return row_rstd(ssq, row); }
;     __device__ __forceinline__ float rstd_global(int row) const { return row_rstd(ssq, row); }
; template <class Epi, class Sched, bool ALIGN_EPI = false, bool SP2 = false>
; __device__ __forceinline__ void gemm_phase(PG8_LAS unsigned char* lds, const Gemm g, const Sched& S, const Epi& E) {
;     ...
;     if constexpr (Epi::RSTD) {
;         PG8_LAS float* rt = (PG8_LAS float*)(lds + STAGE_BYTES);
;         Unit tu;
;         for (int i = 0; S.next(i, tu); ++i) {
;             const int p = tu.pm;
;             if (p != pmc0 && p != pmc1 && p != pmc2 && p != pmc3) {
;                 int slot = -1;
;                 if (pmc0 < 0) { pmc0 = p; slot = 0; } else if (pmc1 < 0) { pmc1 = p; slot = 1; } else if (pmc2 < 0) { pmc2 = p; slot = 2; } else if (pmc3 < 0) { pmc3 = p; slot = 3; }
;                 if (slot >= 0 && tid < 256) rt[slot * 256 + tid] = E.rstd_global(p * 256 + tid);
;             }
;         }
;     }
; __device__ __forceinline__ float row_rstd(const float* ssq, int row) {
;     const float* p = ssq + (size_t)row * 16;
;     const f32x4 a = gld<f32x4>(p), b = gld<f32x4>(p + 4), c = gld<f32x4>(p + 8), d = gld<f32x4>(p + 12);
;     const f32x4 s = (a + b) + (c + d);
;     const float t = (s[0] + s[1]) + (s[2] + s[3]);
;     return __builtin_amdgcn_rsqf(t * (1.f / 1024.f) + RMS_EPS);
; }
.LBB0_223:
	s_andn2_b64 vcc, exec, s[0:1]
	s_cbranch_vccnz .LBB0_323
	v_readlane_b32 s0, v253, 3
	v_mov_b32_e32 v4, v232
	v_readlane_b32 s1, v253, 4
	s_andn2_b64 vcc, exec, s[0:1]
	v_readfirstlane_b32 s4, v4
	s_cbranch_vccnz .LBB0_323
	v_readlane_b32 s2, v254, 39
	s_add_u32 s0, s54, 0x6400000
	v_readlane_b32 s16, v254, 21
	v_lshl_add_u32 v0, v4, 2, s2
	s_movk_i32 s2, 0x100
	v_writelane_b32 v255, s31, 17
	s_addc_u32 s1, s55, 0
	v_cmp_gt_i32_e64 s[12:13], s2, v4
	s_mov_b32 s3, -1
	v_readlane_b32 s17, v254, 22
	s_mov_b32 s11, -1
	s_mov_b32 s18, -1
	s_mov_b32 s10, -1
	s_mov_b32 s101, 0
	s_branch .LBB0_230
.LrsB_ld0:
	v_lshl_add_u32 v2, s2, 8, v4
	v_ashrrev_i32_e32 v3, 31, v2
	v_lshlrev_b64 v[2:3], 6, v[2:3]
	v_lshl_add_u64 v[2:3], s[0:1], 0, v[2:3]
	s_bitset1_b32 s101, 0
	global_load_dwordx4 v[24:27], v[2:3], off
	global_load_dwordx4 v[28:31], v[2:3], off offset:16
	global_load_dwordx4 v[32:35], v[2:3], off offset:32
	global_load_dwordx4 v[36:39], v[2:3], off offset:48
	s_branch .LBB0_227
.LrsB_ld1:
	v_lshl_add_u32 v2, s2, 8, v4
	v_ashrrev_i32_e32 v3, 31, v2
	v_lshlrev_b64 v[2:3], 6, v[2:3]
	v_lshl_add_u64 v[2:3], s[0:1], 0, v[2:3]
	s_bitset1_b32 s101, 1
	global_load_dwordx4 v[40:43], v[2:3], off
	global_load_dwordx4 v[44:47], v[2:3], off offset:16
	global_load_dwordx4 v[48:51], v[2:3], off offset:32
	global_load_dwordx4 v[52:55], v[2:3], off offset:48
	s_branch .LBB0_227
.LrsB_ld2:
	v_lshl_add_u32 v2, s2, 8, v4
	v_ashrrev_i32_e32 v3, 31, v2
	v_lshlrev_b64 v[2:3], 6, v[2:3]
	v_lshl_add_u64 v[2:3], s[0:1], 0, v[2:3]
	s_bitset1_b32 s101, 2
	global_load_dwordx4 v[56:59], v[2:3], off
	global_load_dwordx4 v[60:63], v[2:3], off offset:16
	global_load_dwordx4 v[64:67], v[2:3], off offset:32
	global_load_dwordx4 v[68:71], v[2:3], off offset:48
	s_branch .LBB0_227
.LrsB_ld3:
	v_lshl_add_u32 v2, s2, 8, v4
	v_ashrrev_i32_e32 v3, 31, v2
	v_lshlrev_b64 v[2:3], 6, v[2:3]
	v_lshl_add_u64 v[2:3], s[0:1], 0, v[2:3]
	s_bitset1_b32 s101, 3
	global_load_dwordx4 v[72:75], v[2:3], off
	global_load_dwordx4 v[76:79], v[2:3], off offset:16
	global_load_dwordx4 v[80:83], v[2:3], off offset:32
	global_load_dwordx4 v[84:87], v[2:3], off offset:48

; #define PG8_STAGE(bufoff, gbase, voff) do { _Pragma("unroll") for (int _i = 0; _i < 2; ++_i) \
;         __builtin_amdgcn_global_load_lds((const unsigned*)((const char*)(gbase) + (voff)[_i]), (PG8_LAS unsigned*)(lds + (bufoff) + ldsw + _i * 8192), 16, 0, 0); } while (0)
; #define PG8_WAIT_V(n) asm volatile("s_waitcnt vmcnt(" #n ")" ::: "memory")
; #define PG8_BAR __builtin_amdgcn_s_barrier()
; template <class Epi, class Sched, bool ALIGN_EPI = false, bool SP2 = false>
; __device__ __forceinline__ void gemm_phase(PG8_LAS unsigned char* lds, const Gemm g, const Sched& S, const Epi& E) {
;     ...
;         PG8_STAGE(PG8_SB(0, 0), cB, voffB); PG8_STAGE(PG8_SB(0, 1), cB + hstepB, voffB); PG8_STAGE(PG8_SA(0, 0), cA, voffA); PG8_STAGE(PG8_SA(0, 1), cA + hstepA, voffA);
;         if (wr == 1) PG8_BAR;
;         PG8_WAIT_V(2); PG8_BAR;
;         PG8_STAGE(PG8_SB(1, 0), cB + kstepB, voffB); PG8_STAGE(PG8_SA(1, 0), cA + kstepA, voffA); PG8_STAGE(PG8_SB(1, 1), cB + hstepB + kstepB, voffB);
;         PG8_WAIT_V(6); PG8_BAR;
; __device__ __forceinline__ float row_rstd(const float* ssq, int row) {
;     const float* p = ssq + (size_t)row * 16;
;     const f32x4 a = gld<f32x4>(p), b = gld<f32x4>(p + 4), c = gld<f32x4>(p + 8), d = gld<f32x4>(p + 12);
;     const f32x4 s = (a + b) + (c + d);
;     const float t = (s[0] + s[1]) + (s[2] + s[3]);
;     return __builtin_amdgcn_rsqf(t * (1.f / 1024.f) + RMS_EPS);
; }
.LBB0_244:
	v_and_b32_e32 v11, 48, v4
	v_lshlrev_b32_e32 v12, 6, v4
	s_movk_i32 s11, 0x3c0
	v_lshlrev_b32_e32 v4, 2, v4
	s_lshl_b32 s57, s2, 6
	s_lshl_b32 s2, s2, 13
	v_and_or_b32 v11, v12, s11, v11
	v_and_b32_e32 v4, 32, v4
	v_bitop3_b32 v12, v11, s2, v4 bitop3:0xde
	s_lshl_b32 s2, s3, 5
	s_and_b32 s58, s2, 0x60
	s_add_i32 m0, s22, 0x18000
	v_lshl_add_u64 v[2:3], v[2:3], 0, s[36:37]
	s_lshl_b32 s2, s58, 7
	s_waitcnt vmcnt(2)
	s_barrier
	global_load_lds_dwordx4 v[2:3], off
	s_add_i32 m0, s22, 0x1a000
	v_bitop3_b32 v97, s2, v11, v4 bitop3:0xf6
	s_add_u32 s2, s42, 0x400000
	v_mov_b32_e32 v135, v96
	v_lshl_add_u64 v[0:1], v[0:1], 0, s[36:37]
	s_addc_u32 s3, s43, 0
	s_add_i32 s59, s22, 0x8000
	v_mov_b32_e32 v139, v96
	global_load_lds_dwordx4 v[0:1], off
	v_lshl_add_u64 v[0:1], s[2:3], 0, v[134:135]
	s_mov_b32 m0, s59
	s_add_i32 s96, s22, 0xa000
	global_load_lds_dwordx4 v[0:1], off
	v_lshl_add_u64 v[0:1], s[2:3], 0, v[138:139]
	s_add_u32 s2, s24, 0x40080
	s_mov_b32 m0, s96
	s_addc_u32 s3, s25, 0
	global_load_lds_dwordx4 v[0:1], off
	s_add_i32 m0, s22, 0x1c000
	v_lshl_add_u64 v[0:1], s[2:3], 0, v[136:137]
	global_load_lds_dwordx4 v[0:1], off
	v_lshl_add_u64 v[0:1], s[2:3], 0, v[140:141]
	s_add_i32 m0, s22, 0x1e000
	s_cmpk_lt_u32 s4, 0x100
	global_load_lds_dwordx4 v[0:1], off
	v_lshlrev_b32_e32 v0, 10, v8
	v_and_b32_e32 v0, 0xfffff800, v0
	v_lshl_add_u32 v0, v9, 7, v0
	v_and_b32_e32 v1, 1, v8
	v_lshl_or_b32 v0, v1, 6, v0
	v_lshl_add_u32 v142, v10, 1, v0
	v_lshlrev_b32_e32 v0, 10, v5
	s_cselect_b64 s[2:3], -1, 0
	v_and_b32_e32 v0, 0xfffff800, v0
	s_cmp_eq_u32 s101, 0
	s_cbranch_scc1 .LrsB_done
	v_readlane_b32 s100, v254, 39
	s_waitcnt vmcnt(6)
	s_nop 0
	v_lshl_add_u32 v88, v232, 2, s100
	s_bitcmp1_b32 s101, 0
	s_cbranch_scc0 .LrsB_p1
	v_pk_add_f32 v[26:27], v[26:27], v[30:31]
	v_pk_add_f32 v[24:25], v[24:25], v[28:29]
	v_pk_add_f32 v[34:35], v[34:35], v[38:39]
	v_pk_add_f32 v[32:33], v[32:33], v[36:37]
	v_pk_add_f32 v[26:27], v[26:27], v[34:35]
	v_pk_add_f32 v[24:25], v[24:25], v[32:33]
	s_nop 0
	v_add_f32_e32 v24, v25, v24
	v_add_f32_e32 v26, v26, v27
	v_add_f32_e32 v24, v24, v26
	v_fmamk_f32 v24, v24, 0x3a800000, v251
	v_rsq_f32_e32 v24, v24
	s_nop 1
	ds_write_b32 v88, v24

; #define PG8_STAGE(bufoff, gbase, voff) do { _Pragma("unroll") for (int _i = 0; _i < 2; ++_i) \
;         __builtin_amdgcn_global_load_lds((const unsigned*)((const char*)(gbase) + (voff)[_i]), (PG8_LAS unsigned*)(lds + (bufoff) + ldsw + _i * 8192), 16, 0, 0); } while (0)
; #define PG8_WAIT_V(n) asm volatile("s_waitcnt vmcnt(" #n ")" ::: "memory")
; #define PG8_BAR __builtin_amdgcn_s_barrier()
; template <class Epi, class Sched, bool ALIGN_EPI = false, bool SP2 = false>
; __device__ __forceinline__ void gemm_phase(PG8_LAS unsigned char* lds, const Gemm g, const Sched& S, const Epi& E) {
;     ...
;         PG8_WAIT_V(6); PG8_BAR;
;     } else {
;         PG8_STAGE(PG8_SB(0, 0), cB, voffB); PG8_STAGE(PG8_SA(0, 0), cA, voffA); PG8_STAGE(PG8_SB(0, 1), cB + hstepB, voffB); PG8_STAGE(PG8_SA(0, 1), cA + hstepA, voffA);
;         if (wr == 1) PG8_BAR;
;         PG8_WAIT_V(4); PG8_BAR;
;         PG8_STAGE(PG8_SB(1, 0), cB + kstepB, voffB); PG8_STAGE(PG8_SA(1, 0), cA + kstepA, voffA); PG8_STAGE(PG8_SB(1, 1), cB + hstepB + kstepB, voffB);
;         PG8_WAIT_V(6); PG8_BAR;
;     }
;     for (;;) {
;         const bool has_next = S.next(ui + 1, nxt);
.LrsB_p4:
.LrsB_done:
	s_waitcnt vmcnt(6)
	v_writelane_b32 v255, s2, 33
	v_lshl_add_u32 v0, v6, 7, v0
	v_and_b32_e32 v1, 1, v5
	v_writelane_b32 v255, s3, 34
	v_lshl_or_b32 v0, v1, 6, v0
	v_readlane_b32 s2, v254, 25
	v_mov_b32_e32 v143, v96
	v_lshl_add_u32 v144, v7, 1, v0
	v_mov_b32_e32 v145, v96
	s_mov_b32 s97, 0
	v_add_u32_e32 v151, 0, v12
	s_mov_b32 s4, s2
	v_readlane_b32 s26, v254, 9
	s_barrier
	v_readlane_b32 s3, v254, 26
	s_branch .LBB0_247

; #define PG8_LAS __attribute__((address_space(3)))
;     __device__ __forceinline__ float rstd_global(int row) const { return row_rstd(ssq, row); }
;     __device__ __forceinline__ float rstd_global(int row) const { return row_rstd(ssq, row); }
;     __device__ __forceinline__ float rstd_global(int row) const { return row_rstd(ssq, row); }
; template <class Epi, class Sched, bool ALIGN_EPI = false, bool SP2 = false>
; __device__ __forceinline__ void gemm_phase(PG8_LAS unsigned char* lds, const Gemm g, const Sched& S, const Epi& E) {
;     ...
;     if constexpr (Epi::RSTD) {
;         PG8_LAS float* rt = (PG8_LAS float*)(lds + STAGE_BYTES);
;         Unit tu;
;         for (int i = 0; S.next(i, tu); ++i) {
;             const int p = tu.pm;
;             if (p != pmc0 && p != pmc1 && p != pmc2 && p != pmc3) {
;                 int slot = -1;
;                 if (pmc0 < 0) { pmc0 = p; slot = 0; } else if (pmc1 < 0) { pmc1 = p; slot = 1; } else if (pmc2 < 0) { pmc2 = p; slot = 2; } else if (pmc3 < 0) { pmc3 = p; slot = 3; }
;                 if (slot >= 0 && tid < 256) rt[slot * 256 + tid] = E.rstd_global(p * 256 + tid);
;             }
;         }
;     }
; __device__ __forceinline__ float row_rstd(const float* ssq, int row) {
;     const float* p = ssq + (size_t)row * 16;
;     const f32x4 a = gld<f32x4>(p), b = gld<f32x4>(p + 4), c = gld<f32x4>(p + 8), d = gld<f32x4>(p + 12);
;     const f32x4 s = (a + b) + (c + d);
;     const float t = (s[0] + s[1]) + (s[2] + s[3]);
;     return __builtin_amdgcn_rsqf(t * (1.f / 1024.f) + RMS_EPS);
; }
.LBB0_451:
	s_andn2_b64 vcc, exec, s[0:1]
	s_cbranch_vccnz .LBB0_519
	v_readlane_b32 s0, v253, 8
	v_mov_b32_e32 v4, v232
	v_readlane_b32 s1, v253, 9
	s_andn2_b64 vcc, exec, s[0:1]
	v_readfirstlane_b32 s28, v4
	s_cbranch_vccnz .LBB0_519
	v_writelane_b32 v255, s31, 17
	v_readlane_b32 s16, v254, 21
	v_readlane_b32 s0, v255, 1
	v_readlane_b32 s1, v255, 2
	s_and_b64 s[0:1], s[0:1], exec
	v_readlane_b32 s2, v255, 3
	v_readlane_b32 s3, v255, 4
	s_cselect_b32 s1, 0, s2
	v_readlane_b32 s2, v255, 13
	s_cselect_b32 s0, 0, s3
	s_add_u32 s12, s2, s1
	v_readlane_b32 s1, v255, 14
	s_addc_u32 s13, s1, s0
	v_readlane_b32 s0, v254, 39
	s_mov_b32 s3, -1
	v_readlane_b32 s17, v254, 22
	v_lshl_add_u32 v0, v4, 2, s0
	s_movk_i32 s0, 0x100
	v_cmp_gt_i32_e64 s[0:1], s0, v4
	s_mov_b32 s10, -1
	s_mov_b32 s11, -1
	s_mov_b32 s9, -1
	s_mov_b32 s101, 0
	s_branch .LBB0_458
.LrsC_ld0:
	v_lshl_add_u32 v2, s2, 8, v4
	v_ashrrev_i32_e32 v3, 31, v2
	v_lshlrev_b64 v[2:3], 6, v[2:3]
	v_lshl_add_u64 v[2:3], s[12:13], 0, v[2:3]
	s_bitset1_b32 s101, 0
	global_load_dwordx4 v[24:27], v[2:3], off
	global_load_dwordx4 v[28:31], v[2:3], off offset:16
	global_load_dwordx4 v[32:35], v[2:3], off offset:32
	global_load_dwordx4 v[36:39], v[2:3], off offset:48
	s_branch .LBB0_455
.LrsC_ld1:
	v_lshl_add_u32 v2, s2, 8, v4
	v_ashrrev_i32_e32 v3, 31, v2
	v_lshlrev_b64 v[2:3], 6, v[2:3]
	v_lshl_add_u64 v[2:3], s[12:13], 0, v[2:3]
	s_bitset1_b32 s101, 1
	global_load_dwordx4 v[40:43], v[2:3], off
	global_load_dwordx4 v[44:47], v[2:3], off offset:16
	global_load_dwordx4 v[48:51], v[2:3], off offset:32
	global_load_dwordx4 v[52:55], v[2:3], off offset:48
	s_branch .LBB0_455
.LrsC_ld2:
	v_lshl_add_u32 v2, s2, 8, v4
	v_ashrrev_i32_e32 v3, 31, v2
	v_lshlrev_b64 v[2:3], 6, v[2:3]
	v_lshl_add_u64 v[2:3], s[12:13], 0, v[2:3]
	s_bitset1_b32 s101, 2
	global_load_dwordx4 v[56:59], v[2:3], off
	global_load_dwordx4 v[60:63], v[2:3], off offset:16
	global_load_dwordx4 v[64:67], v[2:3], off offset:32
	global_load_dwordx4 v[68:71], v[2:3], off offset:48
	s_branch .LBB0_455
.LrsC_ld3:
	v_lshl_add_u32 v2, s2, 8, v4
	v_ashrrev_i32_e32 v3, 31, v2
	v_lshlrev_b64 v[2:3], 6, v[2:3]
	v_lshl_add_u64 v[2:3], s[12:13], 0, v[2:3]
	s_bitset1_b32 s101, 3
	global_load_dwordx4 v[72:75], v[2:3], off
	global_load_dwordx4 v[76:79], v[2:3], off offset:16
	global_load_dwordx4 v[80:83], v[2:3], off offset:32
	global_load_dwordx4 v[84:87], v[2:3], off offset:48

; #define PG8_STAGE(bufoff, gbase, voff) do { _Pragma("unroll") for (int _i = 0; _i < 2; ++_i) \
;         __builtin_amdgcn_global_load_lds((const unsigned*)((const char*)(gbase) + (voff)[_i]), (PG8_LAS unsigned*)(lds + (bufoff) + ldsw + _i * 8192), 16, 0, 0); } while (0)
; #define PG8_WAIT_V(n) asm volatile("s_waitcnt vmcnt(" #n ")" ::: "memory")
; #define PG8_BAR __builtin_amdgcn_s_barrier()
; template <class Epi, class Sched, bool ALIGN_EPI = false, bool SP2 = false>
; __device__ __forceinline__ void gemm_phase(PG8_LAS unsigned char* lds, const Gemm g, const Sched& S, const Epi& E) {
;     ...
;         PG8_STAGE(PG8_SB(0, 0), cB, voffB); PG8_STAGE(PG8_SB(0, 1), cB + hstepB, voffB); PG8_STAGE(PG8_SA(0, 0), cA, voffA); PG8_STAGE(PG8_SA(0, 1), cA + hstepA, voffA);
;         if (wr == 1) PG8_BAR;
;         PG8_WAIT_V(2); PG8_BAR;
;         PG8_STAGE(PG8_SB(1, 0), cB + kstepB, voffB); PG8_STAGE(PG8_SA(1, 0), cA + kstepA, voffA); PG8_STAGE(PG8_SB(1, 1), cB + hstepB + kstepB, voffB);
;         PG8_WAIT_V(6); PG8_BAR;
; __device__ __forceinline__ float row_rstd(const float* ssq, int row) {
;     const float* p = ssq + (size_t)row * 16;
;     const f32x4 a = gld<f32x4>(p), b = gld<f32x4>(p + 4), c = gld<f32x4>(p + 8), d = gld<f32x4>(p + 12);
;     const f32x4 s = (a + b) + (c + d);
;     const float t = (s[0] + s[1]) + (s[2] + s[3]);
;     return __builtin_amdgcn_rsqf(t * (1.f / 1024.f) + RMS_EPS);
; }
.LBB0_472:
	s_and_b32 s10, s2, 3
	s_add_i32 m0, s23, 0x18000
	v_lshl_add_u64 v[2:3], v[2:3], 0, s[36:37]
	s_lshl_b32 s48, s3, 6
	s_lshl_b32 s3, s3, 13
	s_lshl_b32 s10, s10, 12
	s_waitcnt vmcnt(2)
	s_barrier
	global_load_lds_dwordx4 v[2:3], off
	s_add_i32 m0, s23, 0x1a000
	s_add_u32 s16, s34, 0x400000
	v_mov_b32_e32 v131, v96
	v_lshl_add_u64 v[0:1], v[0:1], 0, s[36:37]
	s_addc_u32 s17, s35, 0
	s_add_i32 s49, s23, 0x8000
	v_mov_b32_e32 v135, v96
	global_load_lds_dwordx4 v[0:1], off
	v_lshl_add_u64 v[0:1], s[16:17], 0, v[130:131]
	s_mov_b32 m0, s49
	s_add_i32 s50, s23, 0xa000
	global_load_lds_dwordx4 v[0:1], off
	v_lshl_add_u64 v[0:1], s[16:17], 0, v[134:135]
	s_add_u32 s16, s0, 0x40080
	s_mov_b32 m0, s50
	s_addc_u32 s17, s1, 0
	global_load_lds_dwordx4 v[0:1], off
	s_add_i32 m0, s23, 0x1c000
	v_lshl_add_u64 v[0:1], s[16:17], 0, v[132:133]
	global_load_lds_dwordx4 v[0:1], off
	v_lshl_add_u64 v[0:1], s[16:17], 0, v[136:137]
	s_add_i32 m0, s23, 0x1e000
	s_movk_i32 s11, 0x3c0
	global_load_lds_dwordx4 v[0:1], off
	v_and_b32_e32 v0, 48, v4
	v_lshlrev_b32_e32 v1, 6, v4
	v_and_or_b32 v0, v1, s11, v0
	v_lshlrev_b32_e32 v1, 2, v4
	v_and_b32_e32 v1, 32, v1
	v_bitop3_b32 v2, v0, s3, v1 bitop3:0xde
	v_bitop3_b32 v97, v0, s10, v1 bitop3:0xde
	v_lshlrev_b32_e32 v0, 10, v8
	v_and_b32_e32 v0, 0xfffff800, v0
	v_lshl_add_u32 v0, v9, 7, v0
	v_and_b32_e32 v1, 1, v8
	v_lshl_or_b32 v0, v1, 6, v0
	s_cmpk_lt_u32 s28, 0x100
	v_lshl_add_u32 v138, v10, 1, v0
	v_lshlrev_b32_e32 v0, 10, v5
	s_cselect_b64 s[16:17], -1, 0
	s_bfe_u32 s51, s2, 0x10001
	s_lshl_b32 s2, s2, 6
	v_and_b32_e32 v0, 0xfffff800, v0
	s_cmp_eq_u32 s101, 0
	s_cbranch_scc1 .LrsC_done
	v_readlane_b32 s100, v254, 39
	s_waitcnt vmcnt(6)
	s_nop 0
	v_lshl_add_u32 v88, v232, 2, s100
	s_bitcmp1_b32 s101, 0
	s_cbranch_scc0 .LrsC_p1
	v_pk_add_f32 v[26:27], v[26:27], v[30:31]
	v_pk_add_f32 v[24:25], v[24:25], v[28:29]
	v_pk_add_f32 v[34:35], v[34:35], v[38:39]
	v_pk_add_f32 v[32:33], v[32:33], v[36:37]
	v_pk_add_f32 v[26:27], v[26:27], v[34:35]
	v_pk_add_f32 v[24:25], v[24:25], v[32:33]
	s_nop 0
	v_add_f32_e32 v24, v25, v24
	v_add_f32_e32 v26, v26, v27
	v_add_f32_e32 v24, v24, v26
	v_fmamk_f32 v24, v24, 0x3a800000, v251
	v_rsq_f32_e32 v24, v24
	s_nop 1
	ds_write_b32 v88, v24

; #define PG8_STAGE(bufoff, gbase, voff) do { _Pragma("unroll") for (int _i = 0; _i < 2; ++_i) \
;         __builtin_amdgcn_global_load_lds((const unsigned*)((const char*)(gbase) + (voff)[_i]), (PG8_LAS unsigned*)(lds + (bufoff) + ldsw + _i * 8192), 16, 0, 0); } while (0)
; #define PG8_WAIT_V(n) asm volatile("s_waitcnt vmcnt(" #n ")" ::: "memory")
; #define PG8_BAR __builtin_amdgcn_s_barrier()
; template <class Epi, class Sched, bool ALIGN_EPI = false, bool SP2 = false>
; __device__ __forceinline__ void gemm_phase(PG8_LAS unsigned char* lds, const Gemm g, const Sched& S, const Epi& E) {
;     ...
;         PG8_WAIT_V(6); PG8_BAR;
;     } else {
;         PG8_STAGE(PG8_SB(0, 0), cB, voffB); PG8_STAGE(PG8_SA(0, 0), cA, voffA); PG8_STAGE(PG8_SB(0, 1), cB + hstepB, voffB); PG8_STAGE(PG8_SA(0, 1), cA + hstepA, voffA);
;         if (wr == 1) PG8_BAR;
;         PG8_WAIT_V(4); PG8_BAR;
;         PG8_STAGE(PG8_SB(1, 0), cB + kstepB, voffB); PG8_STAGE(PG8_SA(1, 0), cA + kstepA, voffA); PG8_STAGE(PG8_SB(1, 1), cB + hstepB + kstepB, voffB);
;         PG8_WAIT_V(6); PG8_BAR;
;     }
;     for (;;) {
;         const bool has_next = S.next(ui + 1, nxt);
.LrsC_p4:
.LrsC_done:
	s_waitcnt vmcnt(6)
	s_and_b32 s2, s2, 64
	v_readlane_b32 s10, v255, 11
	v_lshl_add_u32 v0, v6, 7, v0
	v_and_b32_e32 v1, 1, v5
	v_readlane_b32 s11, v255, 12
	s_add_u32 s52, s10, s2
	v_lshl_or_b32 v0, v1, 6, v0
	v_readlane_b32 s2, v254, 29
	s_addc_u32 s53, s11, 0
	v_mov_b32_e32 v139, v96
	v_lshl_add_u32 v140, v7, 1, v0
	v_mov_b32_e32 v141, v96
	s_mov_b32 s54, 0
	v_add_u32_e32 v156, 0, v2
	s_mov_b32 s56, s2
	v_readlane_b32 s55, v254, 15
	s_barrier
	v_readlane_b32 s3, v254, 30
	s_branch .LBB0_475
